# diff-attn deferral rebalanced: 14 of 32 score elements deferred into the QK phase (one pair moved back to the PV gaps)
# baseline (speedup 1.0000x reference)
.LBB0_385:
	s_add_i32 s93, s76, -4
	s_add_i32 s92, s72, s76
	s_add_i32 s0, s76, -1
	s_cmp_lt_u32 s0, s82
	s_cselect_b32 s78, s0, s33
	s_add_i32 s91, s76, -2
	s_cmp_lt_u32 s91, s82
	s_cselect_b32 s84, s91, s33
	s_mul_i32 s98, s78, 0x58000
	s_add_u32 s98, s100, s98
	s_addc_u32 s99, s101, 0
	s_and_b32 s0, s77, 0x6000
	s_add_i32 m0, s67, s0
	s_lshl_b64 s[0:1], s[84:85], 7
	s_add_u32 s0, s74, s0
	s_addc_u32 s1, s75, s1
	global_load_lds_dwordx4 v202, s[98:99]
	s_add_i32 s98, s2, 0xc000
	s_and_b32 s98, s98, 0xc000
	s_add_i32 s98, s67, s98
	s_add_i32 m0, s98, 0x8000
	s_nop 0
	global_load_lds_dwordx4 v204, s[0:1]
	s_add_i32 m0, s98, 0xa000
	s_add_u32 s0, s0, 0x400000
	s_addc_u32 s1, s1, 0
	global_load_lds_dwordx4 v204, s[0:1]
	s_and_b32 s0, s2, 0xc000
	s_cmp_le_u32 s93, s83
	v_add_u32_e32 v243, s0, v230
	s_cselect_b64 s[96:97], -1, 0
	s_cmp_gt_u32 s93, s83
	s_mov_b64 s[0:1], -1
	s_cbranch_scc1 .LBB0_389
	s_cmp_eq_u32 s93, 1
	s_cbranch_scc1 .Lmy_oddqk_first
	s_add_i32 s0, s77, 0xffffa000
	s_and_b32 s0, s0, 0x6000
	v_add_u32_e32 v244, s0, v229
	v_add_u32_e32 v245, v244, v232
	ds_read_b128 v[2:5], v245
	ds_read_b128 v[10:13], v241
	ds_read_b128 v[6:9], v245 offset:4096
	v_add_u32_e32 v245, v244, v234
	ds_read_b128 v[18:21], v245
	ds_read_b128 v[14:17], v241 offset:1024
	ds_read_b128 v[22:25], v245 offset:4096
	v_add_u32_e32 v245, v244, v236
	ds_read_b128 v[26:29], v245
	ds_read_b128 v[34:37], v241 offset:2048
	ds_read_b128 v[30:33], v245 offset:4096
	v_add_u32_e32 v245, v244, v238
	ds_read_b128 v[38:41], v245
	ds_read_b128 v[46:49], v241 offset:3072
	ds_read_b128 v[42:45], v245 offset:4096
	s_waitcnt lgkmcnt(10)
	v_mfma_f32_32x32x16_bf16 v[146:161], v[2:5], v[10:13], 0
	s_waitcnt lgkmcnt(9)
	v_mfma_f32_32x32x16_bf16 v[130:145], v[6:9], v[10:13], 0
	v_exp_f32_e32 v246, v52
	v_exp_f32_e32 v247, v53
	v_add_f32_e32 v242, v246, v242
	v_add_f32_e32 v242, v247, v242
	v_cvt_pk_bf16_f32 v171, v246, v247
	s_waitcnt lgkmcnt(7)
	v_mfma_f32_32x32x16_bf16 v[146:161], v[18:21], v[14:17], v[146:161]
	v_exp_f32_e32 v246, v54
	v_exp_f32_e32 v247, v55
	v_add_f32_e32 v242, v246, v242
	v_add_f32_e32 v242, v247, v242
	v_cvt_pk_bf16_f32 v172, v246, v247
	s_waitcnt lgkmcnt(6)
	v_mfma_f32_32x32x16_bf16 v[130:145], v[22:25], v[14:17], v[130:145]
	v_exp_f32_e32 v246, v56
	v_exp_f32_e32 v247, v57
	v_add_f32_e32 v242, v246, v242
	v_add_f32_e32 v242, v247, v242
	v_cvt_pk_bf16_f32 v173, v246, v247
	s_waitcnt lgkmcnt(4)
	v_mfma_f32_32x32x16_bf16 v[146:161], v[26:29], v[34:37], v[146:161]
	v_exp_f32_e32 v246, v58
	v_exp_f32_e32 v247, v59
	v_add_f32_e32 v242, v246, v242
	v_add_f32_e32 v242, v247, v242
	v_cvt_pk_bf16_f32 v174, v246, v247
	s_waitcnt lgkmcnt(3)
	v_mfma_f32_32x32x16_bf16 v[130:145], v[30:33], v[34:37], v[130:145]
	v_exp_f32_e32 v246, v60
	v_exp_f32_e32 v247, v61
	v_add_f32_e32 v242, v246, v242
	v_add_f32_e32 v242, v247, v242
	v_cvt_pk_bf16_f32 v175, v246, v247
	s_waitcnt lgkmcnt(1)
	v_mfma_f32_32x32x16_bf16 v[146:161], v[38:41], v[46:49], v[146:161]
	v_exp_f32_e32 v246, v62
	v_exp_f32_e32 v247, v63
	v_add_f32_e32 v242, v246, v242
	v_add_f32_e32 v242, v247, v242
	v_cvt_pk_bf16_f32 v176, v246, v247
	s_waitcnt lgkmcnt(0)
	v_mfma_f32_32x32x16_bf16 v[130:145], v[42:45], v[46:49], v[130:145]
	v_exp_f32_e32 v246, v64
	v_exp_f32_e32 v247, v65
	v_add_f32_e32 v242, v246, v242
	v_add_f32_e32 v242, v247, v242
	v_cvt_pk_bf16_f32 v177, v246, v247
	s_branch .Lmy_oddqk_join

.LBB0_388:
	v_add_u32_e32 v18, v243, v233
	v_add_u32_e32 v19, v243, v235
	v_add_u32_e32 v20, v243, v237
	v_add_u32_e32 v21, v243, v239
	ds_read_b128 v[2:5], v18 offset:32768
	ds_read_b128 v[6:9], v18 offset:36864
	ds_read_b128 v[10:13], v18 offset:40960
	s_nop 5
	v_exp_f32_e32 v22, v146
	s_waitcnt lgkmcnt(2)
	v_mfma_f32_32x32x16_bf16 v[114:129], v[2:5], v[162:165], v[114:129]
	ds_read_b128 v[14:17], v18 offset:45056
	v_exp_f32_e32 v23, v147
	s_waitcnt lgkmcnt(2)
	v_mfma_f32_32x32x16_bf16 v[98:113], v[6:9], v[162:165], v[98:113]
	ds_read_b128 v[2:5], v19 offset:32768
	v_add_f32_e32 v24, v22, v23
	v_cvt_pk_bf16_f32 v178, v22, v23
	v_exp_f32_e32 v22, v148
	s_waitcnt lgkmcnt(2)
	v_mfma_f32_32x32x16_bf16 v[82:97], v[10:13], v[162:165], v[82:97]
	ds_read_b128 v[6:9], v19 offset:36864
	v_exp_f32_e32 v23, v149
	s_waitcnt lgkmcnt(2)
	v_mfma_f32_32x32x16_bf16 v[66:81], v[14:17], v[162:165], v[66:81]
	ds_read_b128 v[10:13], v19 offset:40960
	v_add_f32_e32 v24, v22, v24
	v_add_f32_e32 v24, v23, v24
	v_cvt_pk_bf16_f32 v179, v22, v23
	v_exp_f32_e32 v22, v150
	s_waitcnt lgkmcnt(2)
	v_mfma_f32_32x32x16_bf16 v[114:129], v[2:5], v[166:169], v[114:129]
	ds_read_b128 v[14:17], v19 offset:45056
	v_exp_f32_e32 v23, v151
	s_waitcnt lgkmcnt(2)
	v_mfma_f32_32x32x16_bf16 v[98:113], v[6:9], v[166:169], v[98:113]
	ds_read_b128 v[2:5], v20 offset:32768
	v_add_f32_e32 v24, v22, v24
	v_add_f32_e32 v24, v23, v24
	v_cvt_pk_bf16_f32 v180, v22, v23
	v_exp_f32_e32 v22, v152
	s_waitcnt lgkmcnt(2)
	v_mfma_f32_32x32x16_bf16 v[82:97], v[10:13], v[166:169], v[82:97]
	ds_read_b128 v[6:9], v20 offset:36864
	v_exp_f32_e32 v23, v153
	s_waitcnt lgkmcnt(2)
	v_mfma_f32_32x32x16_bf16 v[66:81], v[14:17], v[166:169], v[66:81]
	ds_read_b128 v[10:13], v20 offset:40960
	v_add_f32_e32 v24, v22, v24
	v_add_f32_e32 v24, v23, v24
	v_cvt_pk_bf16_f32 v181, v22, v23
	v_exp_f32_e32 v22, v154
	s_waitcnt lgkmcnt(2)
	v_mfma_f32_32x32x16_bf16 v[114:129], v[2:5], v[170:173], v[114:129]
	ds_read_b128 v[14:17], v20 offset:45056
	v_exp_f32_e32 v23, v155
	s_waitcnt lgkmcnt(2)
	v_mfma_f32_32x32x16_bf16 v[98:113], v[6:9], v[170:173], v[98:113]
	ds_read_b128 v[2:5], v21 offset:32768
	v_add_f32_e32 v24, v22, v24
	v_add_f32_e32 v24, v23, v24
	v_cvt_pk_bf16_f32 v146, v22, v23
	v_exp_f32_e32 v22, v156
	s_waitcnt lgkmcnt(2)
	v_mfma_f32_32x32x16_bf16 v[82:97], v[10:13], v[170:173], v[82:97]
	ds_read_b128 v[6:9], v21 offset:36864
	v_exp_f32_e32 v23, v157
	s_waitcnt lgkmcnt(2)
	v_mfma_f32_32x32x16_bf16 v[66:81], v[14:17], v[170:173], v[66:81]
	ds_read_b128 v[10:13], v21 offset:40960
	v_add_f32_e32 v24, v22, v24
	v_add_f32_e32 v24, v23, v24
	v_cvt_pk_bf16_f32 v147, v22, v23
	v_exp_f32_e32 v22, v158
	s_waitcnt lgkmcnt(2)
	v_mfma_f32_32x32x16_bf16 v[114:129], v[2:5], v[174:177], v[114:129]
	ds_read_b128 v[14:17], v21 offset:45056
	v_exp_f32_e32 v23, v159
	s_waitcnt lgkmcnt(2)
	v_mfma_f32_32x32x16_bf16 v[98:113], v[6:9], v[174:177], v[98:113]
	v_add_f32_e32 v24, v22, v24
	v_add_f32_e32 v24, v23, v24
	v_cvt_pk_bf16_f32 v148, v22, v23
	v_exp_f32_e32 v22, v160
	v_exp_f32_e32 v25, v130
	s_waitcnt lgkmcnt(1)
	v_mfma_f32_32x32x16_bf16 v[82:97], v[10:13], v[174:177], v[82:97]
	v_exp_f32_e32 v23, v161
	v_exp_f32_e32 v26, v131
	s_waitcnt lgkmcnt(0)
	v_mfma_f32_32x32x16_bf16 v[66:81], v[14:17], v[174:177], v[66:81]
	v_add_f32_e32 v24, v22, v24
	v_add_f32_e32 v24, v23, v24
	v_cvt_pk_bf16_f32 v149, v22, v23
	v_add_f32_e32 v24, v25, v24
	v_add_f32_e32 v24, v26, v24
	v_cvt_pk_bf16_f32 v150, v25, v26
	v_add_f32_e32 v0, v242, v24
	s_mov_b64 s[0:1], 0
.LBB0_389:
	s_and_b64 vcc, exec, s[0:1]
	s_cbranch_vccz .LBB0_393
	s_add_i32 s0, s76, -5
	s_cmp_gt_u32 s0, s83
	s_cbranch_scc1 .LBB0_392
	s_cmp_eq_u32 s93, 1
	s_cbranch_scc1 .Lmy_odddrain_skip
	v_exp_f32_e32 v246, v52
	v_exp_f32_e32 v247, v53
	v_add_f32_e32 v242, v246, v242
	v_add_f32_e32 v242, v247, v242
	v_cvt_pk_bf16_f32 v171, v246, v247
	v_exp_f32_e32 v246, v54
	v_exp_f32_e32 v247, v55
	v_add_f32_e32 v242, v246, v242
	v_add_f32_e32 v242, v247, v242
	v_cvt_pk_bf16_f32 v172, v246, v247
	v_exp_f32_e32 v246, v56
	v_exp_f32_e32 v247, v57
	v_add_f32_e32 v242, v246, v242
	v_add_f32_e32 v242, v247, v242
	v_cvt_pk_bf16_f32 v173, v246, v247
	v_exp_f32_e32 v246, v58
	v_exp_f32_e32 v247, v59
	v_add_f32_e32 v242, v246, v242
	v_add_f32_e32 v242, v247, v242
	v_cvt_pk_bf16_f32 v174, v246, v247
	v_exp_f32_e32 v246, v60
	v_exp_f32_e32 v247, v61
	v_add_f32_e32 v242, v246, v242
	v_add_f32_e32 v242, v247, v242
	v_cvt_pk_bf16_f32 v175, v246, v247
	v_exp_f32_e32 v246, v62
	v_exp_f32_e32 v247, v63
	v_add_f32_e32 v242, v246, v242
	v_add_f32_e32 v242, v247, v242
	v_cvt_pk_bf16_f32 v176, v246, v247
	v_exp_f32_e32 v246, v64
	v_exp_f32_e32 v247, v65
	v_add_f32_e32 v242, v246, v242
	v_add_f32_e32 v242, v247, v242
	v_cvt_pk_bf16_f32 v177, v246, v247

.LBB0_393:
	s_waitcnt vmcnt(6) lgkmcnt(0)
	s_cmp_ge_u32 s93, s82
	s_barrier
	s_cbranch_scc1 .LBB0_402
	s_cmp_lt_u32 s93, s73
	s_cselect_b32 s0, s76, s33
	s_mul_i32 s98, s0, 0x58000
	s_add_u32 s98, s100, s98
	s_addc_u32 s99, s101, 0
	s_add_i32 s0, s77, 0xffffa000
	s_mov_b32 s79, s85
	s_and_b32 s0, s0, 0x6000
	s_add_i32 m0, s67, s0
	s_lshl_b64 s[0:1], s[78:79], 7
	s_add_u32 s0, s74, s0
	s_addc_u32 s1, s75, s1
	global_load_lds_dwordx4 v202, s[98:99]
	s_add_i32 s98, s2, 0x10000
	s_and_b32 s98, s98, 0xc000
	s_add_i32 s98, s67, s98
	s_add_i32 m0, s98, 0x8000
	s_nop 0
	global_load_lds_dwordx4 v204, s[0:1]
	s_add_i32 m0, s98, 0xa000
	s_add_u32 s0, s0, 0x400000
	s_addc_u32 s1, s1, 0
	global_load_lds_dwordx4 v204, s[0:1]
	s_add_i32 s0, s2, 0x4000
	s_and_b32 s0, s0, 0xc000
	v_add_u32_e32 v248, s0, v230
	s_cmp_ge_u32 s93, s83
	s_mov_b64 s[0:1], -1
	s_cbranch_scc0 .LBB0_398
	s_andn2_b64 vcc, exec, s[96:97]
	s_cbranch_vccnz .LBB0_397
	v_exp_f32_e32 v246, v132
	v_exp_f32_e32 v247, v133
	v_add_f32_e32 v0, v246, v0
	v_add_f32_e32 v0, v247, v0
	v_cvt_pk_bf16_f32 v151, v246, v247
	v_exp_f32_e32 v246, v134
	v_exp_f32_e32 v247, v135
	v_add_f32_e32 v0, v246, v0
	v_add_f32_e32 v0, v247, v0
	v_cvt_pk_bf16_f32 v152, v246, v247
	v_exp_f32_e32 v246, v136
	v_exp_f32_e32 v247, v137
	v_add_f32_e32 v0, v246, v0
	v_add_f32_e32 v0, v247, v0
	v_cvt_pk_bf16_f32 v153, v246, v247
	v_exp_f32_e32 v246, v138
	v_exp_f32_e32 v247, v139
	v_add_f32_e32 v0, v246, v0
	v_add_f32_e32 v0, v247, v0
	v_cvt_pk_bf16_f32 v130, v246, v247
	v_exp_f32_e32 v246, v140
	v_exp_f32_e32 v247, v141
	v_add_f32_e32 v0, v246, v0
	v_add_f32_e32 v0, v247, v0
	v_cvt_pk_bf16_f32 v131, v246, v247
	v_exp_f32_e32 v246, v142
	v_exp_f32_e32 v247, v143
	v_add_f32_e32 v0, v246, v0
	v_add_f32_e32 v0, v247, v0
	v_cvt_pk_bf16_f32 v132, v246, v247
	v_exp_f32_e32 v246, v144
	v_exp_f32_e32 v247, v145
	v_add_f32_e32 v0, v246, v0
	v_add_f32_e32 v0, v247, v0
	v_cvt_pk_bf16_f32 v133, v246, v247
	v_add_u32_e32 v10, v248, v233
	ds_read_b128 v[2:5], v10 offset:32768
	ds_read_b128 v[6:9], v10 offset:36864
	s_waitcnt lgkmcnt(0)
	v_mfma_f32_32x32x16_bf16 v[114:129], v[2:5], v[178:181], v[114:129]
	ds_read_b128 v[2:5], v10 offset:40960
	ds_read_b128 v[136:139], v10 offset:45056
	v_mfma_f32_32x32x16_bf16 v[98:113], v[6:9], v[178:181], v[98:113]
	s_waitcnt lgkmcnt(0)
	v_mfma_f32_32x32x16_bf16 v[82:97], v[2:5], v[178:181], v[82:97]
	v_mfma_f32_32x32x16_bf16 v[66:81], v[136:139], v[178:181], v[66:81]
	v_add_u32_e32 v135, v248, v235
	ds_read_b128 v[136:139], v135 offset:32768
	s_waitcnt lgkmcnt(0)
	v_mfma_f32_32x32x16_bf16 v[114:129], v[136:139], v[146:149], v[114:129]
	ds_read_b128 v[136:139], v135 offset:36864
	s_waitcnt lgkmcnt(0)
	v_mfma_f32_32x32x16_bf16 v[98:113], v[136:139], v[146:149], v[98:113]
	ds_read_b128 v[136:139], v135 offset:40960
	s_waitcnt lgkmcnt(0)
	v_mfma_f32_32x32x16_bf16 v[82:97], v[136:139], v[146:149], v[82:97]
	ds_read_b128 v[136:139], v135 offset:45056
	s_waitcnt lgkmcnt(0)
	v_mfma_f32_32x32x16_bf16 v[66:81], v[136:139], v[146:149], v[66:81]
	v_add_u32_e32 v135, v248, v237
	ds_read_b128 v[136:139], v135 offset:32768
	s_waitcnt lgkmcnt(0)
	v_mfma_f32_32x32x16_bf16 v[114:129], v[136:139], v[150:153], v[114:129]
	ds_read_b128 v[136:139], v135 offset:36864
	s_waitcnt lgkmcnt(0)
	v_mfma_f32_32x32x16_bf16 v[98:113], v[136:139], v[150:153], v[98:113]
	ds_read_b128 v[136:139], v135 offset:40960
	s_waitcnt lgkmcnt(0)
	v_mfma_f32_32x32x16_bf16 v[82:97], v[136:139], v[150:153], v[82:97]
	ds_read_b128 v[136:139], v135 offset:45056
	s_waitcnt lgkmcnt(0)
	v_mfma_f32_32x32x16_bf16 v[66:81], v[136:139], v[150:153], v[66:81]
	v_add_u32_e32 v135, v248, v239
	ds_read_b128 v[136:139], v135 offset:32768
	s_waitcnt lgkmcnt(0)
	v_mfma_f32_32x32x16_bf16 v[114:129], v[136:139], v[130:133], v[114:129]
	ds_read_b128 v[136:139], v135 offset:36864
	s_waitcnt lgkmcnt(0)
	v_mfma_f32_32x32x16_bf16 v[98:113], v[136:139], v[130:133], v[98:113]
	ds_read_b128 v[136:139], v135 offset:40960
	s_waitcnt lgkmcnt(0)
	v_mfma_f32_32x32x16_bf16 v[82:97], v[136:139], v[130:133], v[82:97]
	ds_read_b128 v[136:139], v135 offset:45056
	s_waitcnt lgkmcnt(0)
	v_mfma_f32_32x32x16_bf16 v[66:81], v[136:139], v[130:133], v[66:81]

.LBB0_398:
	s_andn2_b64 vcc, exec, s[0:1]
	s_cbranch_vccnz .LBB0_403
	s_add_i32 s0, s77, 0xffffc000
	s_and_b32 s0, s0, 0x6000
	v_add_u32_e32 v244, s0, v229
	v_add_u32_e32 v245, v244, v232
	ds_read_b128 v[2:5], v245
	ds_read_b128 v[162:165], v241
	ds_read_b128 v[6:9], v245 offset:4096
	v_add_u32_e32 v245, v244, v234
	ds_read_b128 v[10:13], v245
	ds_read_b128 v[166:169], v241 offset:1024
	ds_read_b128 v[14:17], v245 offset:4096
	v_add_u32_e32 v245, v244, v236
	ds_read_b128 v[18:21], v245
	ds_read_b128 v[170:173], v241 offset:2048
	ds_read_b128 v[22:25], v245 offset:4096
	v_add_u32_e32 v245, v244, v238
	ds_read_b128 v[26:29], v245
	ds_read_b128 v[174:177], v241 offset:3072
	ds_read_b128 v[30:33], v245 offset:4096
	s_waitcnt lgkmcnt(10)
	v_mfma_f32_32x32x16_bf16 v[34:49], v[2:5], v[162:165], 0
	s_waitcnt lgkmcnt(9)
	v_mfma_f32_32x32x16_bf16 v[50:65], v[6:9], v[162:165], 0
	v_exp_f32_e32 v246, v132
	v_exp_f32_e32 v247, v133
	v_add_f32_e32 v0, v246, v0
	v_add_f32_e32 v0, v247, v0
	v_cvt_pk_bf16_f32 v151, v246, v247
	s_waitcnt lgkmcnt(7)
	v_mfma_f32_32x32x16_bf16 v[34:49], v[10:13], v[166:169], v[34:49]
	v_exp_f32_e32 v246, v134
	v_exp_f32_e32 v247, v135
	v_add_f32_e32 v0, v246, v0
	v_add_f32_e32 v0, v247, v0
	v_cvt_pk_bf16_f32 v152, v246, v247
	s_waitcnt lgkmcnt(6)
	v_mfma_f32_32x32x16_bf16 v[50:65], v[14:17], v[166:169], v[50:65]
	v_exp_f32_e32 v246, v136
	v_exp_f32_e32 v247, v137
	v_add_f32_e32 v0, v246, v0
	v_add_f32_e32 v0, v247, v0
	v_cvt_pk_bf16_f32 v153, v246, v247
	s_waitcnt lgkmcnt(4)
	v_mfma_f32_32x32x16_bf16 v[34:49], v[18:21], v[170:173], v[34:49]
	v_exp_f32_e32 v246, v138
	v_exp_f32_e32 v247, v139
	v_add_f32_e32 v0, v246, v0
	v_add_f32_e32 v0, v247, v0
	v_cvt_pk_bf16_f32 v130, v246, v247
	s_waitcnt lgkmcnt(3)
	v_mfma_f32_32x32x16_bf16 v[50:65], v[22:25], v[170:173], v[50:65]
	v_exp_f32_e32 v246, v140
	v_exp_f32_e32 v247, v141
	v_add_f32_e32 v0, v246, v0
	v_add_f32_e32 v0, v247, v0
	v_cvt_pk_bf16_f32 v131, v246, v247
	s_waitcnt lgkmcnt(1)
	v_mfma_f32_32x32x16_bf16 v[34:49], v[26:29], v[174:177], v[34:49]
	v_exp_f32_e32 v246, v142
	v_exp_f32_e32 v247, v143
	v_add_f32_e32 v0, v246, v0
	v_add_f32_e32 v0, v247, v0
	v_cvt_pk_bf16_f32 v132, v246, v247
	s_waitcnt lgkmcnt(0)
	v_mfma_f32_32x32x16_bf16 v[50:65], v[30:33], v[174:177], v[50:65]
	v_exp_f32_e32 v246, v144
	v_exp_f32_e32 v247, v145
	v_add_f32_e32 v0, v246, v0
	v_add_f32_e32 v0, v247, v0
	v_cvt_pk_bf16_f32 v133, v246, v247
	s_cmp_lg_u32 s92, 3
	s_cbranch_scc1 .LBB0_401
	v_mov_b32_e32 v18, v240
	s_nop 0
	v_cmp_gt_i32_e64 s[62:63], 22, v18
	v_cmp_gt_i32_e64 s[64:65], 23, v18
	v_cmp_gt_i32_e64 s[60:61], 21, v18
	s_and_b64 s[62:63], s[64:65], s[62:63]
	v_cmp_gt_i32_e64 s[58:59], 20, v18
	s_and_b64 s[60:61], s[62:63], s[60:61]
	v_cmp_gt_i32_e64 s[56:57], 19, v18
	s_and_b64 s[58:59], s[60:61], s[58:59]
	v_cmp_gt_i32_e64 s[54:55], 18, v18
	s_and_b64 s[56:57], s[58:59], s[56:57]
	v_cmp_gt_i32_e64 s[52:53], 17, v18
	s_and_b64 s[54:55], s[56:57], s[54:55]
	v_cmp_gt_i32_e64 s[50:51], 16, v18
	s_and_b64 s[52:53], s[54:55], s[52:53]
	v_cmp_gt_i32_e64 s[48:49], 7, v18
	s_and_b64 s[50:51], s[52:53], s[50:51]
	v_cmp_gt_i32_e64 s[46:47], 6, v18
	s_and_b64 s[48:49], s[50:51], s[48:49]
	v_cmp_gt_i32_e64 s[44:45], 5, v18
	s_and_b64 s[46:47], s[48:49], s[46:47]
	v_cmp_gt_i32_e64 s[42:43], 4, v18
	s_and_b64 s[44:45], s[46:47], s[44:45]
	v_cmp_gt_i32_e64 s[40:41], 3, v18
	s_and_b64 s[42:43], s[44:45], s[42:43]
	v_cmp_gt_i32_e64 s[38:39], 2, v18
	s_and_b64 s[40:41], s[42:43], s[40:41]
	v_cmp_gt_i32_e64 s[36:37], 1, v18
	s_and_b64 s[38:39], s[40:41], s[38:39]
	v_cmp_gt_i32_e64 s[34:35], 0, v18
	s_and_b64 s[36:37], s[38:39], s[36:37]
	s_and_b64 s[34:35], s[36:37], s[34:35]
	v_cmp_gt_i32_e64 s[30:31], 54, v18
	v_cndmask_b32_e64 v34, v34, v227, s[34:35]
	v_cmp_gt_i32_e64 s[34:35], 55, v18
	v_cmp_gt_i32_e64 s[28:29], 53, v18
	s_and_b64 s[30:31], s[34:35], s[30:31]
	v_cmp_gt_i32_e64 s[26:27], 52, v18
	s_and_b64 s[28:29], s[30:31], s[28:29]
	v_cmp_gt_i32_e64 s[24:25], 51, v18
	s_and_b64 s[26:27], s[28:29], s[26:27]
	v_cmp_gt_i32_e64 s[22:23], 50, v18
	s_and_b64 s[24:25], s[26:27], s[24:25]
	v_cmp_gt_i32_e64 s[20:21], 49, v18
	s_and_b64 s[22:23], s[24:25], s[22:23]
	v_cmp_gt_i32_e64 s[18:19], 48, v18
	s_and_b64 s[20:21], s[22:23], s[20:21]
	v_cmp_gt_i32_e64 s[16:17], 39, v18
	s_and_b64 s[18:19], s[20:21], s[18:19]
	v_cmp_gt_i32_e64 s[14:15], 38, v18
	s_and_b64 s[16:17], s[18:19], s[16:17]
	v_cmp_gt_i32_e64 s[12:13], 37, v18
	s_and_b64 s[14:15], s[16:17], s[14:15]
	v_cmp_gt_i32_e64 s[10:11], 36, v18
	s_and_b64 s[12:13], s[14:15], s[12:13]
	v_cmp_gt_i32_e64 s[8:9], 35, v18
	s_and_b64 s[10:11], s[12:13], s[10:11]
	v_cmp_gt_i32_e64 s[6:7], 34, v18
	s_and_b64 s[8:9], s[10:11], s[8:9]
	v_cmp_gt_i32_e64 s[0:1], 33, v18
	s_and_b64 s[6:7], s[8:9], s[6:7]
	v_cmp_gt_i32_e32 vcc, 32, v18
	s_and_b64 s[0:1], s[6:7], s[0:1]
	s_and_b64 vcc, s[0:1], vcc
	v_cndmask_b32_e64 v49, v49, v227, s[64:65]
	v_cndmask_b32_e64 v48, v48, v227, s[62:63]
	v_cndmask_b32_e64 v47, v47, v227, s[60:61]
	v_cndmask_b32_e64 v46, v46, v227, s[58:59]
	v_cndmask_b32_e64 v45, v45, v227, s[56:57]
	v_cndmask_b32_e64 v44, v44, v227, s[54:55]
	v_cndmask_b32_e64 v43, v43, v227, s[52:53]
	v_cndmask_b32_e64 v42, v42, v227, s[50:51]
	v_cndmask_b32_e64 v41, v41, v227, s[48:49]
	v_cndmask_b32_e64 v40, v40, v227, s[46:47]
	v_cndmask_b32_e64 v39, v39, v227, s[44:45]
	v_cndmask_b32_e64 v38, v38, v227, s[42:43]
	v_cndmask_b32_e64 v37, v37, v227, s[40:41]
	v_cndmask_b32_e64 v36, v36, v227, s[38:39]
	v_cndmask_b32_e64 v35, v35, v227, s[36:37]
	v_cndmask_b32_e64 v65, v65, v227, s[34:35]
	v_cndmask_b32_e64 v64, v64, v227, s[30:31]
	v_cndmask_b32_e64 v63, v63, v227, s[28:29]
	v_cndmask_b32_e64 v62, v62, v227, s[26:27]
	v_cndmask_b32_e64 v61, v61, v227, s[24:25]
	v_cndmask_b32_e64 v60, v60, v227, s[22:23]
	v_cndmask_b32_e64 v59, v59, v227, s[20:21]
	v_cndmask_b32_e64 v58, v58, v227, s[18:19]
	v_cndmask_b32_e64 v57, v57, v227, s[16:17]
	v_cndmask_b32_e64 v56, v56, v227, s[14:15]
	v_cndmask_b32_e64 v55, v55, v227, s[12:13]
	v_cndmask_b32_e64 v54, v54, v227, s[10:11]
	v_cndmask_b32_e64 v53, v53, v227, s[8:9]
	v_cndmask_b32_e64 v52, v52, v227, s[6:7]
	v_cndmask_b32_e64 v51, v51, v227, s[0:1]
	v_cndmask_b32_e32 v50, v50, v227, vcc
.LBB0_401:
	v_add_u32_e32 v18, v248, v233
	v_add_u32_e32 v19, v248, v235
	v_add_u32_e32 v20, v248, v237
	v_add_u32_e32 v21, v248, v239
	ds_read_b128 v[2:5], v18 offset:32768
	ds_read_b128 v[6:9], v18 offset:36864
	ds_read_b128 v[10:13], v18 offset:40960
	s_nop 5
	v_exp_f32_e32 v22, v34
	s_waitcnt lgkmcnt(2)
	v_mfma_f32_32x32x16_bf16 v[114:129], v[2:5], v[178:181], v[114:129]
	ds_read_b128 v[14:17], v18 offset:45056
	v_exp_f32_e32 v23, v35
	s_waitcnt lgkmcnt(2)
	v_mfma_f32_32x32x16_bf16 v[98:113], v[6:9], v[178:181], v[98:113]
	ds_read_b128 v[2:5], v19 offset:32768
	v_add_f32_e32 v24, v22, v23
	v_cvt_pk_bf16_f32 v162, v22, v23
	v_exp_f32_e32 v22, v36
	s_waitcnt lgkmcnt(2)
	v_mfma_f32_32x32x16_bf16 v[82:97], v[10:13], v[178:181], v[82:97]
	ds_read_b128 v[6:9], v19 offset:36864
	v_exp_f32_e32 v23, v37
	s_waitcnt lgkmcnt(2)
	v_mfma_f32_32x32x16_bf16 v[66:81], v[14:17], v[178:181], v[66:81]
	ds_read_b128 v[10:13], v19 offset:40960
	v_add_f32_e32 v24, v22, v24
	v_add_f32_e32 v24, v23, v24
	v_cvt_pk_bf16_f32 v163, v22, v23
	v_exp_f32_e32 v22, v38
	s_waitcnt lgkmcnt(2)
	v_mfma_f32_32x32x16_bf16 v[114:129], v[2:5], v[146:149], v[114:129]
	ds_read_b128 v[14:17], v19 offset:45056
	v_exp_f32_e32 v23, v39
	s_waitcnt lgkmcnt(2)
	v_mfma_f32_32x32x16_bf16 v[98:113], v[6:9], v[146:149], v[98:113]
	ds_read_b128 v[2:5], v20 offset:32768
	v_add_f32_e32 v24, v22, v24
	v_add_f32_e32 v24, v23, v24
	v_cvt_pk_bf16_f32 v164, v22, v23
	v_exp_f32_e32 v22, v40
	s_waitcnt lgkmcnt(2)
	v_mfma_f32_32x32x16_bf16 v[82:97], v[10:13], v[146:149], v[82:97]
	ds_read_b128 v[6:9], v20 offset:36864
	v_exp_f32_e32 v23, v41
	s_waitcnt lgkmcnt(2)
	v_mfma_f32_32x32x16_bf16 v[66:81], v[14:17], v[146:149], v[66:81]
	ds_read_b128 v[10:13], v20 offset:40960
	v_add_f32_e32 v24, v22, v24
	v_add_f32_e32 v24, v23, v24
	v_cvt_pk_bf16_f32 v165, v22, v23
	v_exp_f32_e32 v22, v42
	s_waitcnt lgkmcnt(2)
	v_mfma_f32_32x32x16_bf16 v[114:129], v[2:5], v[150:153], v[114:129]
	ds_read_b128 v[14:17], v20 offset:45056
	v_exp_f32_e32 v23, v43
	s_waitcnt lgkmcnt(2)
	v_mfma_f32_32x32x16_bf16 v[98:113], v[6:9], v[150:153], v[98:113]
	ds_read_b128 v[2:5], v21 offset:32768
	v_add_f32_e32 v24, v22, v24
	v_add_f32_e32 v24, v23, v24
	v_cvt_pk_bf16_f32 v166, v22, v23
	v_exp_f32_e32 v22, v44
	s_waitcnt lgkmcnt(2)
	v_mfma_f32_32x32x16_bf16 v[82:97], v[10:13], v[150:153], v[82:97]
	ds_read_b128 v[6:9], v21 offset:36864
	v_exp_f32_e32 v23, v45
	s_waitcnt lgkmcnt(2)
	v_mfma_f32_32x32x16_bf16 v[66:81], v[14:17], v[150:153], v[66:81]
	ds_read_b128 v[10:13], v21 offset:40960
	v_add_f32_e32 v24, v22, v24
	v_add_f32_e32 v24, v23, v24
	v_cvt_pk_bf16_f32 v167, v22, v23
	v_exp_f32_e32 v22, v46
	s_waitcnt lgkmcnt(2)
	v_mfma_f32_32x32x16_bf16 v[114:129], v[2:5], v[130:133], v[114:129]
	ds_read_b128 v[14:17], v21 offset:45056
	v_exp_f32_e32 v23, v47
	s_waitcnt lgkmcnt(2)
	v_mfma_f32_32x32x16_bf16 v[98:113], v[6:9], v[130:133], v[98:113]
	v_add_f32_e32 v24, v22, v24
	v_add_f32_e32 v24, v23, v24
	v_cvt_pk_bf16_f32 v168, v22, v23
	v_exp_f32_e32 v22, v48
	v_exp_f32_e32 v25, v50
	s_waitcnt lgkmcnt(1)
	v_mfma_f32_32x32x16_bf16 v[82:97], v[10:13], v[130:133], v[82:97]
	v_exp_f32_e32 v23, v49
	v_exp_f32_e32 v26, v51
	s_waitcnt lgkmcnt(0)
	v_mfma_f32_32x32x16_bf16 v[66:81], v[14:17], v[130:133], v[66:81]
	v_add_f32_e32 v24, v22, v24
	v_add_f32_e32 v24, v23, v24
	v_cvt_pk_bf16_f32 v169, v22, v23
	v_add_f32_e32 v24, v25, v24
	v_add_f32_e32 v24, v26, v24
	v_cvt_pk_bf16_f32 v170, v25, v26
	v_add_f32_e32 v242, v0, v24
	s_branch .LBB0_404
